# MFMA order: both K-steps of each accumulator adjacent (SrcC forwarding) in FFN-in, w_in, resid K-loops
# speedup vs baseline: 1.0033x; 1.0033x over previous
.LBB0_143:
	s_add_u32 s26, s16, 0xfffc0080
	s_addc_u32 s27, s17, -1
	s_add_i32 s34, 0, 0x10000
	s_cmp_eq_u32 s37, 12
	s_cselect_b32 s31, s9, s27
	s_cselect_b32 s30, s25, s26
	v_add_u32_e32 v138, s34, v141
	s_cselect_b32 s27, s7, s36
	s_cselect_b32 s26, s28, s29
	s_add_i32 s40, 0, 0x14000
	ds_read_b128 v[144:147], v138
	ds_read_b128 v[148:151], v138 offset:1024
	ds_read_b128 v[152:155], v138 offset:2048
	ds_read_b128 v[156:159], v138 offset:3072
	v_add_u32_e32 v138, s40, v141
	ds_read_b128 v[160:163], v138
	ds_read_b128 v[164:167], v138 offset:1024
	ds_read_b128 v[168:171], v138 offset:2048
	ds_read_b128 v[172:175], v138 offset:3072
	v_lshl_add_u64 v[138:139], s[16:17], 0, v[132:133]
	s_add_i32 m0, s53, 0xc000
	ds_read_b128 v[176:179], v143
	ds_read_b128 v[180:183], v143 offset:1024
	ds_read_b128 v[184:187], v143 offset:2048
	ds_read_b128 v[188:191], v143 offset:3072
	ds_read_b128 v[192:195], v143 offset:4096
	ds_read_b128 v[196:199], v143 offset:5120
	ds_read_b128 v[200:203], v143 offset:6144
	ds_read_b128 v[204:207], v143 offset:7168
	global_load_lds_dwordx4 v[138:139], off
	v_lshl_add_u64 v[138:139], s[16:17], 0, v[134:135]
	s_add_i32 m0, s53, 0xe000
	s_nop 0
	global_load_lds_dwordx4 v[138:139], off
	s_waitcnt vmcnt(8)
	s_waitcnt lgkmcnt(0)
	s_barrier
	s_setprio 1
	s_waitcnt lgkmcnt(0)
	v_mfma_f32_16x16x32_bf16 v[126:129], v[144:147], v[176:179], v[126:129]
	v_mfma_f32_16x16x32_bf16 v[126:129], v[148:151], v[180:183], v[126:129]
	v_mfma_f32_16x16x32_bf16 v[118:121], v[152:155], v[176:179], v[118:121]
	v_mfma_f32_16x16x32_bf16 v[118:121], v[156:159], v[180:183], v[118:121]
	v_mfma_f32_16x16x32_bf16 v[110:113], v[144:147], v[184:187], v[110:113]
	v_mfma_f32_16x16x32_bf16 v[110:113], v[148:151], v[188:191], v[110:113]
	v_mfma_f32_16x16x32_bf16 v[102:105], v[152:155], v[184:187], v[102:105]
	v_mfma_f32_16x16x32_bf16 v[102:105], v[156:159], v[188:191], v[102:105]
	v_mfma_f32_16x16x32_bf16 v[94:97], v[144:147], v[192:195], v[94:97]
	v_mfma_f32_16x16x32_bf16 v[94:97], v[148:151], v[196:199], v[94:97]
	v_mfma_f32_16x16x32_bf16 v[86:89], v[152:155], v[192:195], v[86:89]
	v_mfma_f32_16x16x32_bf16 v[86:89], v[156:159], v[196:199], v[86:89]
	v_mfma_f32_16x16x32_bf16 v[78:81], v[144:147], v[200:203], v[78:81]
	v_mfma_f32_16x16x32_bf16 v[78:81], v[148:151], v[204:207], v[78:81]
	v_mfma_f32_16x16x32_bf16 v[70:73], v[152:155], v[200:203], v[70:73]
	v_mfma_f32_16x16x32_bf16 v[70:73], v[156:159], v[204:207], v[70:73]
	s_setprio 0
	s_setprio 1
	v_mfma_f32_16x16x32_bf16 v[122:125], v[160:163], v[176:179], v[122:125]
	v_mfma_f32_16x16x32_bf16 v[122:125], v[164:167], v[180:183], v[122:125]
	v_mfma_f32_16x16x32_bf16 v[114:117], v[168:171], v[176:179], v[114:117]
	v_mfma_f32_16x16x32_bf16 v[114:117], v[172:175], v[180:183], v[114:117]
	v_mfma_f32_16x16x32_bf16 v[106:109], v[160:163], v[184:187], v[106:109]
	v_mfma_f32_16x16x32_bf16 v[106:109], v[164:167], v[188:191], v[106:109]
	v_mfma_f32_16x16x32_bf16 v[98:101], v[168:171], v[184:187], v[98:101]
	v_mfma_f32_16x16x32_bf16 v[98:101], v[172:175], v[188:191], v[98:101]
	v_mfma_f32_16x16x32_bf16 v[90:93], v[160:163], v[192:195], v[90:93]
	v_mfma_f32_16x16x32_bf16 v[90:93], v[164:167], v[196:199], v[90:93]
	v_mfma_f32_16x16x32_bf16 v[82:85], v[168:171], v[192:195], v[82:85]
	v_mfma_f32_16x16x32_bf16 v[82:85], v[172:175], v[196:199], v[82:85]
	v_mfma_f32_16x16x32_bf16 v[74:77], v[160:163], v[200:203], v[74:77]
	v_mfma_f32_16x16x32_bf16 v[74:77], v[164:167], v[204:207], v[74:77]
	v_mfma_f32_16x16x32_bf16 v[66:69], v[168:171], v[200:203], v[66:69]
	v_mfma_f32_16x16x32_bf16 v[66:69], v[172:175], v[204:207], v[66:69]
	s_setprio 0
	s_barrier
	s_add_i32 s34, s34, s47
	v_lshl_add_u64 v[138:139], s[26:27], 0, v[0:1]
	s_mov_b32 m0, s34
	ds_read_b128 v[176:179], v143 offset:16384
	ds_read_b128 v[180:183], v143 offset:17408
	ds_read_b128 v[184:187], v143 offset:18432
	ds_read_b128 v[188:191], v143 offset:19456
	ds_read_b128 v[192:195], v143 offset:20480
	ds_read_b128 v[196:199], v143 offset:21504
	ds_read_b128 v[200:203], v143 offset:22528
	ds_read_b128 v[204:207], v143 offset:23552
	global_load_lds_dwordx4 v[138:139], off
	s_add_i32 m0, s34, 0x2000
	s_add_u32 s34, s26, 0x40000
	v_lshl_add_u64 v[208:209], s[26:27], 0, v[130:131]
	s_addc_u32 s35, s27, 0
	s_add_i32 s40, s40, s47
	global_load_lds_dwordx4 v[208:209], off
	v_lshl_add_u64 v[222:223], s[34:35], 0, v[0:1]
	s_mov_b32 m0, s40
	v_lshl_add_u64 v[224:225], s[30:31], 0, v[130:131]
	global_load_lds_dwordx4 v[222:223], off
	v_lshl_add_u64 v[222:223], s[34:35], 0, v[130:131]
	s_add_i32 m0, s40, 0x2000
	s_nop 0
	global_load_lds_dwordx4 v[222:223], off
	v_lshl_add_u64 v[222:223], s[30:31], 0, v[0:1]
	s_mov_b32 m0, s53
	s_nop 0
	global_load_lds_dwordx4 v[222:223], off
	s_mov_b32 m0, s64
	s_nop 0
	global_load_lds_dwordx4 v[224:225], off
	s_waitcnt vmcnt(8)
	s_waitcnt lgkmcnt(0)
	s_barrier
	s_setprio 1
	s_waitcnt lgkmcnt(0)
	v_mfma_f32_16x16x32_bf16 v[62:65], v[144:147], v[176:179], v[62:65]
	v_mfma_f32_16x16x32_bf16 v[62:65], v[148:151], v[180:183], v[62:65]
	v_mfma_f32_16x16x32_bf16 v[54:57], v[152:155], v[176:179], v[54:57]
	v_mfma_f32_16x16x32_bf16 v[54:57], v[156:159], v[180:183], v[54:57]
	v_mfma_f32_16x16x32_bf16 v[46:49], v[144:147], v[184:187], v[46:49]
	v_mfma_f32_16x16x32_bf16 v[46:49], v[148:151], v[188:191], v[46:49]
	v_mfma_f32_16x16x32_bf16 v[38:41], v[152:155], v[184:187], v[38:41]
	v_mfma_f32_16x16x32_bf16 v[38:41], v[156:159], v[188:191], v[38:41]
	v_mfma_f32_16x16x32_bf16 v[30:33], v[144:147], v[192:195], v[30:33]
	v_mfma_f32_16x16x32_bf16 v[30:33], v[148:151], v[196:199], v[30:33]
	v_mfma_f32_16x16x32_bf16 v[22:25], v[152:155], v[192:195], v[22:25]
	v_mfma_f32_16x16x32_bf16 v[22:25], v[156:159], v[196:199], v[22:25]
	v_mfma_f32_16x16x32_bf16 v[14:17], v[144:147], v[200:203], v[14:17]
	v_mfma_f32_16x16x32_bf16 v[14:17], v[148:151], v[204:207], v[14:17]
	v_mfma_f32_16x16x32_bf16 v[6:9], v[152:155], v[200:203], v[6:9]
	v_mfma_f32_16x16x32_bf16 v[6:9], v[156:159], v[204:207], v[6:9]
	s_setprio 0
	s_setprio 1
	v_mfma_f32_16x16x32_bf16 v[58:61], v[160:163], v[176:179], v[58:61]
	v_mfma_f32_16x16x32_bf16 v[58:61], v[164:167], v[180:183], v[58:61]
	v_mfma_f32_16x16x32_bf16 v[50:53], v[168:171], v[176:179], v[50:53]
	v_mfma_f32_16x16x32_bf16 v[50:53], v[172:175], v[180:183], v[50:53]
	v_mfma_f32_16x16x32_bf16 v[42:45], v[160:163], v[184:187], v[42:45]
	v_mfma_f32_16x16x32_bf16 v[42:45], v[164:167], v[188:191], v[42:45]
	v_mfma_f32_16x16x32_bf16 v[34:37], v[168:171], v[184:187], v[34:37]
	v_mfma_f32_16x16x32_bf16 v[34:37], v[172:175], v[188:191], v[34:37]
	v_mfma_f32_16x16x32_bf16 v[26:29], v[160:163], v[192:195], v[26:29]
	v_mfma_f32_16x16x32_bf16 v[26:29], v[164:167], v[196:199], v[26:29]
	v_mfma_f32_16x16x32_bf16 v[18:21], v[168:171], v[192:195], v[18:21]
	v_mfma_f32_16x16x32_bf16 v[18:21], v[172:175], v[196:199], v[18:21]
	v_mfma_f32_16x16x32_bf16 v[10:13], v[160:163], v[200:203], v[10:13]
	v_mfma_f32_16x16x32_bf16 v[10:13], v[164:167], v[204:207], v[10:13]
	v_mfma_f32_16x16x32_bf16 v[2:5], v[168:171], v[200:203], v[2:5]
	v_mfma_f32_16x16x32_bf16 v[2:5], v[172:175], v[204:207], v[2:5]
	s_setprio 0
	s_barrier
	s_add_i32 s34, 0, 0x18000
	s_add_i32 s35, 0, 0x1c000
	v_add_u32_e32 v156, s34, v141
	v_add_u32_e32 v172, s35, v141
	ds_read_b128 v[144:147], v156
	ds_read_b128 v[148:151], v156 offset:1024
	ds_read_b128 v[152:155], v156 offset:2048
	ds_read_b128 v[156:159], v156 offset:3072
	ds_read_b128 v[160:163], v172
	ds_read_b128 v[164:167], v172 offset:1024
	ds_read_b128 v[168:171], v172 offset:2048
	ds_read_b128 v[172:175], v172 offset:3072
	s_add_u32 s30, s30, 0x40000
	s_addc_u32 s31, s31, 0
	s_mov_b32 m0, s65
	v_lshl_add_u64 v[226:227], s[30:31], 0, v[0:1]
	ds_read_b128 v[176:179], v143 offset:32768
	ds_read_b128 v[180:183], v143 offset:33792
	ds_read_b128 v[184:187], v143 offset:34816
	ds_read_b128 v[188:191], v143 offset:35840
	ds_read_b128 v[192:195], v143 offset:36864
	ds_read_b128 v[196:199], v143 offset:37888
	ds_read_b128 v[200:203], v143 offset:38912
	ds_read_b128 v[204:207], v143 offset:39936
	global_load_lds_dwordx4 v[226:227], off
	v_lshl_add_u64 v[226:227], s[30:31], 0, v[130:131]
	s_mov_b32 m0, s68
	s_nop 0
	global_load_lds_dwordx4 v[226:227], off
	s_waitcnt vmcnt(8)
	s_waitcnt lgkmcnt(0)
	s_barrier
	s_setprio 1
	s_waitcnt lgkmcnt(0)
	v_mfma_f32_16x16x32_bf16 v[126:129], v[144:147], v[176:179], v[126:129]
	v_mfma_f32_16x16x32_bf16 v[126:129], v[148:151], v[180:183], v[126:129]
	v_mfma_f32_16x16x32_bf16 v[118:121], v[152:155], v[176:179], v[118:121]
	v_mfma_f32_16x16x32_bf16 v[118:121], v[156:159], v[180:183], v[118:121]
	v_mfma_f32_16x16x32_bf16 v[110:113], v[144:147], v[184:187], v[110:113]
	v_mfma_f32_16x16x32_bf16 v[110:113], v[148:151], v[188:191], v[110:113]
	v_mfma_f32_16x16x32_bf16 v[102:105], v[152:155], v[184:187], v[102:105]
	v_mfma_f32_16x16x32_bf16 v[102:105], v[156:159], v[188:191], v[102:105]
	v_mfma_f32_16x16x32_bf16 v[94:97], v[144:147], v[192:195], v[94:97]
	v_mfma_f32_16x16x32_bf16 v[94:97], v[148:151], v[196:199], v[94:97]
	v_mfma_f32_16x16x32_bf16 v[86:89], v[152:155], v[192:195], v[86:89]
	v_mfma_f32_16x16x32_bf16 v[86:89], v[156:159], v[196:199], v[86:89]
	v_mfma_f32_16x16x32_bf16 v[78:81], v[144:147], v[200:203], v[78:81]
	v_mfma_f32_16x16x32_bf16 v[78:81], v[148:151], v[204:207], v[78:81]
	v_mfma_f32_16x16x32_bf16 v[70:73], v[152:155], v[200:203], v[70:73]
	v_mfma_f32_16x16x32_bf16 v[70:73], v[156:159], v[204:207], v[70:73]
	s_setprio 0
	s_setprio 1
	v_mfma_f32_16x16x32_bf16 v[122:125], v[160:163], v[176:179], v[122:125]
	v_mfma_f32_16x16x32_bf16 v[122:125], v[164:167], v[180:183], v[122:125]
	v_mfma_f32_16x16x32_bf16 v[114:117], v[168:171], v[176:179], v[114:117]
	v_mfma_f32_16x16x32_bf16 v[114:117], v[172:175], v[180:183], v[114:117]
	v_mfma_f32_16x16x32_bf16 v[106:109], v[160:163], v[184:187], v[106:109]
	v_mfma_f32_16x16x32_bf16 v[106:109], v[164:167], v[188:191], v[106:109]
	v_mfma_f32_16x16x32_bf16 v[98:101], v[168:171], v[184:187], v[98:101]
	v_mfma_f32_16x16x32_bf16 v[98:101], v[172:175], v[188:191], v[98:101]
	v_mfma_f32_16x16x32_bf16 v[90:93], v[160:163], v[192:195], v[90:93]
	v_mfma_f32_16x16x32_bf16 v[90:93], v[164:167], v[196:199], v[90:93]
	v_mfma_f32_16x16x32_bf16 v[82:85], v[168:171], v[192:195], v[82:85]
	v_mfma_f32_16x16x32_bf16 v[82:85], v[172:175], v[196:199], v[82:85]
	v_mfma_f32_16x16x32_bf16 v[74:77], v[160:163], v[200:203], v[74:77]
	v_mfma_f32_16x16x32_bf16 v[74:77], v[164:167], v[204:207], v[74:77]
	v_mfma_f32_16x16x32_bf16 v[66:69], v[168:171], v[200:203], v[66:69]
	v_mfma_f32_16x16x32_bf16 v[66:69], v[172:175], v[204:207], v[66:69]
	s_setprio 0
	s_barrier
	s_add_i32 s30, s34, s47
	v_lshl_add_u64 v[138:139], v[138:139], 0, s[22:23]
	s_mov_b32 m0, s30
	ds_read_b128 v[176:179], v143 offset:49152
	ds_read_b128 v[180:183], v143 offset:50176
	ds_read_b128 v[184:187], v143 offset:51200
	ds_read_b128 v[188:191], v143 offset:52224
	ds_read_b128 v[192:195], v143 offset:53248
	ds_read_b128 v[196:199], v143 offset:54272
	ds_read_b128 v[200:203], v143 offset:55296
	ds_read_b128 v[204:207], v143 offset:56320
	global_load_lds_dwordx4 v[138:139], off
	s_add_i32 m0, s30, 0x2000
	s_add_u32 s26, s26, 0x40080
	v_lshl_add_u64 v[138:139], v[208:209], 0, s[22:23]
	s_addc_u32 s27, s27, 0
	s_add_i32 s30, s35, s47
	global_load_lds_dwordx4 v[138:139], off
	v_lshl_add_u64 v[138:139], s[26:27], 0, v[0:1]
	s_mov_b32 m0, s30
	s_nop 0
	global_load_lds_dwordx4 v[138:139], off
	v_lshl_add_u64 v[138:139], s[26:27], 0, v[130:131]
	s_add_i32 m0, s30, 0x2000
	s_nop 0
	global_load_lds_dwordx4 v[138:139], off
	v_lshl_add_u64 v[138:139], v[222:223], 0, s[22:23]
	s_mov_b32 m0, s69
	s_nop 0
	global_load_lds_dwordx4 v[138:139], off
	v_lshl_add_u64 v[138:139], v[224:225], 0, s[22:23]
	s_mov_b32 m0, s70
	s_nop 0
	global_load_lds_dwordx4 v[138:139], off
	s_waitcnt vmcnt(8)
	s_waitcnt lgkmcnt(0)
	s_barrier
	s_setprio 1
	s_waitcnt lgkmcnt(0)
	v_mfma_f32_16x16x32_bf16 v[62:65], v[144:147], v[176:179], v[62:65]
	v_mfma_f32_16x16x32_bf16 v[62:65], v[148:151], v[180:183], v[62:65]
	v_mfma_f32_16x16x32_bf16 v[54:57], v[152:155], v[176:179], v[54:57]
	v_mfma_f32_16x16x32_bf16 v[54:57], v[156:159], v[180:183], v[54:57]
	v_mfma_f32_16x16x32_bf16 v[46:49], v[144:147], v[184:187], v[46:49]
	v_mfma_f32_16x16x32_bf16 v[46:49], v[148:151], v[188:191], v[46:49]
	v_mfma_f32_16x16x32_bf16 v[38:41], v[152:155], v[184:187], v[38:41]
	v_mfma_f32_16x16x32_bf16 v[38:41], v[156:159], v[188:191], v[38:41]
	v_mfma_f32_16x16x32_bf16 v[30:33], v[144:147], v[192:195], v[30:33]
	v_mfma_f32_16x16x32_bf16 v[30:33], v[148:151], v[196:199], v[30:33]
	v_mfma_f32_16x16x32_bf16 v[22:25], v[152:155], v[192:195], v[22:25]
	v_mfma_f32_16x16x32_bf16 v[22:25], v[156:159], v[196:199], v[22:25]
	v_mfma_f32_16x16x32_bf16 v[14:17], v[144:147], v[200:203], v[14:17]
	v_mfma_f32_16x16x32_bf16 v[14:17], v[148:151], v[204:207], v[14:17]
	v_mfma_f32_16x16x32_bf16 v[6:9], v[152:155], v[200:203], v[6:9]
	v_mfma_f32_16x16x32_bf16 v[6:9], v[156:159], v[204:207], v[6:9]
	s_setprio 0
	s_setprio 1
	v_mfma_f32_16x16x32_bf16 v[58:61], v[160:163], v[176:179], v[58:61]
	v_mfma_f32_16x16x32_bf16 v[58:61], v[164:167], v[180:183], v[58:61]
	v_mfma_f32_16x16x32_bf16 v[50:53], v[168:171], v[176:179], v[50:53]
	v_mfma_f32_16x16x32_bf16 v[50:53], v[172:175], v[180:183], v[50:53]
	v_mfma_f32_16x16x32_bf16 v[42:45], v[160:163], v[184:187], v[42:45]
	v_mfma_f32_16x16x32_bf16 v[42:45], v[164:167], v[188:191], v[42:45]
	v_mfma_f32_16x16x32_bf16 v[34:37], v[168:171], v[184:187], v[34:37]
	v_mfma_f32_16x16x32_bf16 v[34:37], v[172:175], v[188:191], v[34:37]
	v_mfma_f32_16x16x32_bf16 v[26:29], v[160:163], v[192:195], v[26:29]
	v_mfma_f32_16x16x32_bf16 v[26:29], v[164:167], v[196:199], v[26:29]
	v_mfma_f32_16x16x32_bf16 v[18:21], v[168:171], v[192:195], v[18:21]
	v_mfma_f32_16x16x32_bf16 v[18:21], v[172:175], v[196:199], v[18:21]
	v_mfma_f32_16x16x32_bf16 v[10:13], v[160:163], v[200:203], v[10:13]
	v_mfma_f32_16x16x32_bf16 v[10:13], v[164:167], v[204:207], v[10:13]
	v_mfma_f32_16x16x32_bf16 v[2:5], v[168:171], v[200:203], v[2:5]
	v_mfma_f32_16x16x32_bf16 v[2:5], v[172:175], v[204:207], v[2:5]
	s_setprio 0
	s_barrier
	s_add_i32 s37, s37, 2
	s_add_u32 s16, s16, 0x100
	s_addc_u32 s17, s17, 0
	s_add_u32 s29, s29, 0x100
	s_addc_u32 s36, s36, 0
	s_cmp_gt_u32 s37, 13
	s_cbranch_scc0 .LBB0_143
	s_and_b64 vcc, exec, s[2:3]
	s_cbranch_vccz .LBB0_146
	s_barrier
.LBB0_146:
	v_mul_f32_e32 v145, 0xbfb8aa3b, v126
	v_exp_f32_e32 v145, v145
	v_lshl_or_b32 v146, s15, 7, v142
	v_lshl_add_u32 v144, s14, 8, v140
	v_ashrrev_i32_e32 v147, 31, v146
	v_add_f32_e32 v145, 1.0, v145
	v_rcp_f32_e32 v145, v145
	v_mov_b64_e32 v[138:139], s[86:87]
	v_mad_i64_i32 v[148:149], s[14:15], v144, s72, v[138:139]
	v_mul_f32_e32 v126, v126, v145
	v_mul_f32_e32 v122, v126, v122
	v_mul_f32_e32 v126, 0xbfb8aa3b, v127
	v_exp_f32_e32 v126, v126
	v_readlane_b32 s36, v255, 31
	s_andn2_b64 vcc, exec, s[4:5]
	v_readlane_b32 s37, v255, 32
	v_add_f32_e32 v126, 1.0, v126
	v_rcp_f32_e32 v126, v126
	s_nop 0
	v_mul_f32_e32 v126, v127, v126
	v_mul_f32_e32 v123, v126, v123
	v_mul_f32_e32 v126, 0xbfb8aa3b, v128
	v_exp_f32_e32 v126, v126
	s_nop 0
	v_add_f32_e32 v126, 1.0, v126
	v_rcp_f32_e32 v126, v126
	s_nop 0
	v_mul_f32_e32 v126, v128, v126
	v_mul_f32_e32 v124, v126, v124
	v_mul_f32_e32 v126, 0xbfb8aa3b, v129
	v_exp_f32_e32 v126, v126
	s_nop 0
	v_add_f32_e32 v126, 1.0, v126
	v_rcp_f32_e32 v126, v126
	s_nop 0
	v_mul_f32_e32 v126, v129, v126
	v_mul_f32_e32 v125, v126, v125
	v_mul_f32_e32 v126, 0xbfb8aa3b, v118
	v_exp_f32_e32 v126, v126
	s_nop 0
	v_add_f32_e32 v126, 1.0, v126
	v_rcp_f32_e32 v126, v126
	s_nop 0
	v_mul_f32_e32 v118, v118, v126
	v_mul_f32_e32 v118, v118, v114
	v_mul_f32_e32 v114, 0xbfb8aa3b, v119
	v_exp_f32_e32 v114, v114
	s_nop 0
	v_add_f32_e32 v114, 1.0, v114
	v_rcp_f32_e32 v114, v114
	s_nop 0
	v_mul_f32_e32 v114, v119, v114
	v_mul_f32_e32 v119, v114, v115
	v_mul_f32_e32 v114, 0xbfb8aa3b, v120
	v_exp_f32_e32 v114, v114
	s_nop 0
	v_add_f32_e32 v114, 1.0, v114
	v_rcp_f32_e32 v114, v114
	s_nop 0
	v_mul_f32_e32 v114, v120, v114
	v_mul_f32_e32 v126, v114, v116
	v_mul_f32_e32 v114, 0xbfb8aa3b, v121
	v_exp_f32_e32 v114, v114
	v_cvt_pk_bf16_f32 v116, v122, v123
	s_nop 0
	v_add_f32_e32 v114, 1.0, v114
	v_rcp_f32_e32 v114, v114
	s_nop 0
	v_mul_f32_e32 v114, v121, v114
	v_mul_f32_e32 v127, v114, v117
	v_lshlrev_b64 v[114:115], 1, v[146:147]
	v_lshl_add_u64 v[120:121], v[148:149], 0, v[114:115]
	v_cvt_pk_bf16_f32 v117, v124, v125
	v_cvt_pk_bf16_f32 v118, v118, v119
	v_cvt_pk_bf16_f32 v119, v126, v127
	global_store_dwordx4 v[120:121], v[116:119], off
	s_nop 1
	v_mul_f32_e32 v118, 0xbfb8aa3b, v110
	v_exp_f32_e32 v118, v118
	v_or_b32_e32 v116, 16, v144
	v_mad_i64_i32 v[116:117], s[14:15], v116, s72, v[138:139]
	v_add_f32_e32 v118, 1.0, v118
	v_rcp_f32_e32 v118, v118
	s_nop 0
	v_mul_f32_e32 v110, v110, v118
	v_mul_f32_e32 v106, v110, v106
	v_mul_f32_e32 v110, 0xbfb8aa3b, v111
	v_exp_f32_e32 v110, v110
	s_nop 0
	v_add_f32_e32 v110, 1.0, v110
	v_rcp_f32_e32 v110, v110
	s_nop 0
	v_mul_f32_e32 v110, v111, v110
	v_mul_f32_e32 v107, v110, v107
	v_mul_f32_e32 v110, 0xbfb8aa3b, v112
	v_exp_f32_e32 v110, v110
	s_nop 0
	v_add_f32_e32 v110, 1.0, v110
	v_rcp_f32_e32 v110, v110
	s_nop 0
	v_mul_f32_e32 v110, v112, v110
	v_mul_f32_e32 v108, v110, v108
	v_mul_f32_e32 v110, 0xbfb8aa3b, v113
	v_exp_f32_e32 v110, v110
	s_nop 0
	v_add_f32_e32 v110, 1.0, v110
	v_rcp_f32_e32 v110, v110
	s_nop 0
	v_mul_f32_e32 v110, v113, v110
	v_mul_f32_e32 v109, v110, v109
	v_mul_f32_e32 v110, 0xbfb8aa3b, v102
	v_exp_f32_e32 v110, v110
	s_nop 0
	v_add_f32_e32 v110, 1.0, v110
	v_rcp_f32_e32 v110, v110
	s_nop 0
	v_mul_f32_e32 v102, v102, v110
	v_mul_f32_e32 v110, v102, v98
	v_mul_f32_e32 v98, 0xbfb8aa3b, v103
	v_exp_f32_e32 v98, v98
	s_nop 0
	v_add_f32_e32 v98, 1.0, v98
	v_rcp_f32_e32 v98, v98
	s_nop 0
	v_mul_f32_e32 v98, v103, v98
	v_mul_f32_e32 v111, v98, v99
	v_mul_f32_e32 v98, 0xbfb8aa3b, v104
	v_exp_f32_e32 v98, v98
	v_lshl_add_u64 v[102:103], v[116:117], 0, v[114:115]
	v_add_f32_e32 v98, 1.0, v98
	v_rcp_f32_e32 v98, v98
	s_nop 0
	v_mul_f32_e32 v98, v104, v98
	v_mul_f32_e32 v104, v98, v100
	v_mul_f32_e32 v98, 0xbfb8aa3b, v105
	v_exp_f32_e32 v98, v98
	s_nop 0
	v_add_f32_e32 v98, 1.0, v98
	v_rcp_f32_e32 v98, v98
	s_nop 0
	v_mul_f32_e32 v98, v105, v98
	v_mul_f32_e32 v101, v98, v101
	v_cvt_pk_bf16_f32 v98, v106, v107
	v_cvt_pk_bf16_f32 v99, v108, v109
	v_cvt_pk_bf16_f32 v100, v110, v111
	v_cvt_pk_bf16_f32 v101, v104, v101
	global_store_dwordx4 v[102:103], v[98:101], off
	s_nop 1
	v_mul_f32_e32 v100, 0xbfb8aa3b, v94
	v_exp_f32_e32 v100, v100
	v_or_b32_e32 v98, 32, v144
	v_mad_i64_i32 v[98:99], s[14:15], v98, s72, v[138:139]
	v_add_f32_e32 v100, 1.0, v100
	v_rcp_f32_e32 v100, v100
	s_nop 0
	v_mul_f32_e32 v94, v94, v100
	v_mul_f32_e32 v90, v94, v90
	v_mul_f32_e32 v94, 0xbfb8aa3b, v95
	v_exp_f32_e32 v94, v94
	s_nop 0
	v_add_f32_e32 v94, 1.0, v94
	v_rcp_f32_e32 v94, v94
	s_nop 0
	v_mul_f32_e32 v94, v95, v94
	v_mul_f32_e32 v91, v94, v91
	v_mul_f32_e32 v94, 0xbfb8aa3b, v96
	v_exp_f32_e32 v94, v94
	s_nop 0
	v_add_f32_e32 v94, 1.0, v94
	v_rcp_f32_e32 v94, v94
	s_nop 0
	v_mul_f32_e32 v94, v96, v94
	v_mul_f32_e32 v92, v94, v92
	v_mul_f32_e32 v94, 0xbfb8aa3b, v97
	v_exp_f32_e32 v94, v94
	s_nop 0
	v_add_f32_e32 v94, 1.0, v94
	v_rcp_f32_e32 v94, v94
	s_nop 0
	v_mul_f32_e32 v94, v97, v94
	v_mul_f32_e32 v93, v94, v93
	v_mul_f32_e32 v94, 0xbfb8aa3b, v86
	v_exp_f32_e32 v94, v94
	s_nop 0
	v_add_f32_e32 v94, 1.0, v94
	v_rcp_f32_e32 v94, v94
	s_nop 0
	v_mul_f32_e32 v86, v86, v94
	v_mul_f32_e32 v94, v86, v82
	v_mul_f32_e32 v82, 0xbfb8aa3b, v87
	v_exp_f32_e32 v82, v82
	s_nop 0
	v_add_f32_e32 v82, 1.0, v82
	v_rcp_f32_e32 v82, v82
	s_nop 0
	v_mul_f32_e32 v82, v87, v82
	v_mul_f32_e32 v95, v82, v83
	v_mul_f32_e32 v82, 0xbfb8aa3b, v88
	v_exp_f32_e32 v82, v82
	v_lshl_add_u64 v[86:87], v[98:99], 0, v[114:115]
	v_add_f32_e32 v82, 1.0, v82
	v_rcp_f32_e32 v82, v82
	s_nop 0
	v_mul_f32_e32 v82, v88, v82
	v_mul_f32_e32 v88, v82, v84
	v_mul_f32_e32 v82, 0xbfb8aa3b, v89
	v_exp_f32_e32 v82, v82
	s_nop 0
	v_add_f32_e32 v82, 1.0, v82
	v_rcp_f32_e32 v82, v82
	s_nop 0
	v_mul_f32_e32 v82, v89, v82
	v_mul_f32_e32 v85, v82, v85
	v_cvt_pk_bf16_f32 v82, v90, v91
	v_cvt_pk_bf16_f32 v83, v92, v93
	v_cvt_pk_bf16_f32 v84, v94, v95
	v_cvt_pk_bf16_f32 v85, v88, v85
	global_store_dwordx4 v[86:87], v[82:85], off
	s_nop 1
	v_mul_f32_e32 v84, 0xbfb8aa3b, v78
	v_exp_f32_e32 v84, v84
	v_or_b32_e32 v82, 48, v144
	v_mad_i64_i32 v[82:83], s[14:15], v82, s72, v[138:139]
	v_add_f32_e32 v84, 1.0, v84
	v_rcp_f32_e32 v84, v84
	s_nop 0
	v_mul_f32_e32 v78, v78, v84
	v_mul_f32_e32 v74, v78, v74
	v_mul_f32_e32 v78, 0xbfb8aa3b, v79
	v_exp_f32_e32 v78, v78
	s_nop 0
	v_add_f32_e32 v78, 1.0, v78
	v_rcp_f32_e32 v78, v78
	s_nop 0
	v_mul_f32_e32 v78, v79, v78
	v_mul_f32_e32 v75, v78, v75
	v_mul_f32_e32 v78, 0xbfb8aa3b, v80
	v_exp_f32_e32 v78, v78
	s_nop 0
	v_add_f32_e32 v78, 1.0, v78
	v_rcp_f32_e32 v78, v78
	s_nop 0
	v_mul_f32_e32 v78, v80, v78
	v_mul_f32_e32 v76, v78, v76
	v_mul_f32_e32 v78, 0xbfb8aa3b, v81
	v_exp_f32_e32 v78, v78
	s_nop 0
	v_add_f32_e32 v78, 1.0, v78
	v_rcp_f32_e32 v78, v78
	s_nop 0
	v_mul_f32_e32 v78, v81, v78
	v_mul_f32_e32 v77, v78, v77
	v_mul_f32_e32 v78, 0xbfb8aa3b, v70
	v_exp_f32_e32 v78, v78
	s_nop 0
	v_add_f32_e32 v78, 1.0, v78
	v_rcp_f32_e32 v78, v78
	s_nop 0
	v_mul_f32_e32 v70, v70, v78
	v_mul_f32_e32 v78, v70, v66
	v_mul_f32_e32 v66, 0xbfb8aa3b, v71
	v_exp_f32_e32 v66, v66
	s_nop 0
	v_add_f32_e32 v66, 1.0, v66
	v_rcp_f32_e32 v66, v66
	s_nop 0
	v_mul_f32_e32 v66, v71, v66
	v_mul_f32_e32 v79, v66, v67
	v_mul_f32_e32 v66, 0xbfb8aa3b, v72
	v_exp_f32_e32 v66, v66
	v_lshl_add_u64 v[70:71], v[82:83], 0, v[114:115]
	v_add_f32_e32 v66, 1.0, v66
	v_rcp_f32_e32 v66, v66
	s_nop 0
	v_mul_f32_e32 v66, v72, v66
	v_mul_f32_e32 v72, v66, v68
	v_mul_f32_e32 v66, 0xbfb8aa3b, v73
	v_exp_f32_e32 v66, v66
	s_nop 0
	v_add_f32_e32 v66, 1.0, v66
	v_rcp_f32_e32 v66, v66
	s_nop 0
	v_mul_f32_e32 v66, v73, v66
	v_mul_f32_e32 v69, v66, v69
	v_cvt_pk_bf16_f32 v66, v74, v75
	v_cvt_pk_bf16_f32 v67, v76, v77
	v_cvt_pk_bf16_f32 v68, v78, v79
	v_cvt_pk_bf16_f32 v69, v72, v69
	global_store_dwordx4 v[70:71], v[66:69], off
	s_nop 1
	v_mul_f32_e32 v68, 0xbfb8aa3b, v62
	v_exp_f32_e32 v68, v68
	v_add_u32_e32 v66, 0x80, v144
	v_mad_i64_i32 v[66:67], s[14:15], v66, s72, v[138:139]
	v_add_f32_e32 v68, 1.0, v68
	v_rcp_f32_e32 v68, v68
	s_nop 0
	v_mul_f32_e32 v62, v62, v68
	v_mul_f32_e32 v58, v62, v58
	v_mul_f32_e32 v62, 0xbfb8aa3b, v63
	v_exp_f32_e32 v62, v62
	s_nop 0
	v_add_f32_e32 v62, 1.0, v62
	v_rcp_f32_e32 v62, v62
	s_nop 0
	v_mul_f32_e32 v62, v63, v62
	v_mul_f32_e32 v59, v62, v59
	v_mul_f32_e32 v62, 0xbfb8aa3b, v64
	v_exp_f32_e32 v62, v62
	s_nop 0
	v_add_f32_e32 v62, 1.0, v62
	v_rcp_f32_e32 v62, v62
	s_nop 0
	v_mul_f32_e32 v62, v64, v62
	v_mul_f32_e32 v60, v62, v60
	v_mul_f32_e32 v62, 0xbfb8aa3b, v65
	v_exp_f32_e32 v62, v62
	s_nop 0
	v_add_f32_e32 v62, 1.0, v62
	v_rcp_f32_e32 v62, v62
	s_nop 0
	v_mul_f32_e32 v62, v65, v62
	v_mul_f32_e32 v61, v62, v61
	v_mul_f32_e32 v62, 0xbfb8aa3b, v54
	v_exp_f32_e32 v62, v62
	s_nop 0
	v_add_f32_e32 v62, 1.0, v62
	v_rcp_f32_e32 v62, v62
	s_nop 0
	v_mul_f32_e32 v54, v54, v62
	v_mul_f32_e32 v62, v54, v50
	v_mul_f32_e32 v50, 0xbfb8aa3b, v55
	v_exp_f32_e32 v50, v50
	s_nop 0
	v_add_f32_e32 v50, 1.0, v50
	v_rcp_f32_e32 v50, v50
	s_nop 0
	v_mul_f32_e32 v50, v55, v50
	v_mul_f32_e32 v63, v50, v51
	v_mul_f32_e32 v50, 0xbfb8aa3b, v56
	v_exp_f32_e32 v50, v50
	v_lshl_add_u64 v[54:55], v[66:67], 0, v[114:115]
	v_add_f32_e32 v50, 1.0, v50
	v_rcp_f32_e32 v50, v50
	s_nop 0
	v_mul_f32_e32 v50, v56, v50
	v_mul_f32_e32 v56, v50, v52
	v_mul_f32_e32 v50, 0xbfb8aa3b, v57
	v_exp_f32_e32 v50, v50
	s_nop 0
	v_add_f32_e32 v50, 1.0, v50
	v_rcp_f32_e32 v50, v50
	s_nop 0
	v_mul_f32_e32 v50, v57, v50
	v_mul_f32_e32 v53, v50, v53
	v_cvt_pk_bf16_f32 v50, v58, v59
	v_cvt_pk_bf16_f32 v51, v60, v61
	v_cvt_pk_bf16_f32 v52, v62, v63
	v_cvt_pk_bf16_f32 v53, v56, v53
	global_store_dwordx4 v[54:55], v[50:53], off
	s_nop 1
	v_mul_f32_e32 v52, 0xbfb8aa3b, v46
	v_exp_f32_e32 v52, v52
	v_add_u32_e32 v50, 0x90, v144
	v_mad_i64_i32 v[50:51], s[14:15], v50, s72, v[138:139]
	v_add_f32_e32 v52, 1.0, v52
	v_rcp_f32_e32 v52, v52
	s_nop 0
	v_mul_f32_e32 v46, v46, v52
	v_mul_f32_e32 v42, v46, v42
	v_mul_f32_e32 v46, 0xbfb8aa3b, v47
	v_exp_f32_e32 v46, v46
	s_nop 0
	v_add_f32_e32 v46, 1.0, v46
	v_rcp_f32_e32 v46, v46
	s_nop 0
	v_mul_f32_e32 v46, v47, v46
	v_mul_f32_e32 v43, v46, v43
	v_mul_f32_e32 v46, 0xbfb8aa3b, v48
	v_exp_f32_e32 v46, v46
	s_nop 0
	v_add_f32_e32 v46, 1.0, v46
	v_rcp_f32_e32 v46, v46
	s_nop 0
	v_mul_f32_e32 v46, v48, v46
	v_mul_f32_e32 v44, v46, v44
	v_mul_f32_e32 v46, 0xbfb8aa3b, v49
	v_exp_f32_e32 v46, v46
	s_nop 0
	v_add_f32_e32 v46, 1.0, v46
	v_rcp_f32_e32 v46, v46
	s_nop 0
	v_mul_f32_e32 v46, v49, v46
	v_mul_f32_e32 v45, v46, v45
	v_mul_f32_e32 v46, 0xbfb8aa3b, v38
	v_exp_f32_e32 v46, v46
	s_nop 0
	v_add_f32_e32 v46, 1.0, v46
	v_rcp_f32_e32 v46, v46
	s_nop 0
	v_mul_f32_e32 v38, v38, v46
	v_mul_f32_e32 v46, v38, v34
	v_mul_f32_e32 v34, 0xbfb8aa3b, v39
	v_exp_f32_e32 v34, v34
	s_nop 0
	v_add_f32_e32 v34, 1.0, v34
	v_rcp_f32_e32 v34, v34
	s_nop 0
	v_mul_f32_e32 v34, v39, v34
	v_mul_f32_e32 v47, v34, v35
	v_mul_f32_e32 v34, 0xbfb8aa3b, v40
	v_exp_f32_e32 v34, v34
	v_lshl_add_u64 v[38:39], v[50:51], 0, v[114:115]
	v_add_f32_e32 v34, 1.0, v34
	v_rcp_f32_e32 v34, v34
	s_nop 0
	v_mul_f32_e32 v34, v40, v34
	v_mul_f32_e32 v40, v34, v36
	v_mul_f32_e32 v34, 0xbfb8aa3b, v41
	v_exp_f32_e32 v34, v34
	s_nop 0
	v_add_f32_e32 v34, 1.0, v34
	v_rcp_f32_e32 v34, v34
	s_nop 0
	v_mul_f32_e32 v34, v41, v34
	v_mul_f32_e32 v37, v34, v37
	v_cvt_pk_bf16_f32 v34, v42, v43
	v_cvt_pk_bf16_f32 v35, v44, v45
	v_cvt_pk_bf16_f32 v36, v46, v47
	v_cvt_pk_bf16_f32 v37, v40, v37
	global_store_dwordx4 v[38:39], v[34:37], off
	s_nop 1
	v_mul_f32_e32 v36, 0xbfb8aa3b, v30
	v_exp_f32_e32 v36, v36
	v_add_u32_e32 v34, 0xa0, v144
	v_mad_i64_i32 v[34:35], s[14:15], v34, s72, v[138:139]
	v_add_f32_e32 v36, 1.0, v36
	v_rcp_f32_e32 v36, v36
	s_nop 0
	v_mul_f32_e32 v30, v30, v36
	v_mul_f32_e32 v26, v30, v26
	v_mul_f32_e32 v30, 0xbfb8aa3b, v31
	v_exp_f32_e32 v30, v30
	s_nop 0
	v_add_f32_e32 v30, 1.0, v30
	v_rcp_f32_e32 v30, v30
	s_nop 0
	v_mul_f32_e32 v30, v31, v30
	v_mul_f32_e32 v27, v30, v27
	v_mul_f32_e32 v30, 0xbfb8aa3b, v32
	v_exp_f32_e32 v30, v30
	s_nop 0
	v_add_f32_e32 v30, 1.0, v30
	v_rcp_f32_e32 v30, v30
	s_nop 0
	v_mul_f32_e32 v30, v32, v30
	v_mul_f32_e32 v28, v30, v28
	v_mul_f32_e32 v30, 0xbfb8aa3b, v33
	v_exp_f32_e32 v30, v30
	s_nop 0
	v_add_f32_e32 v30, 1.0, v30
	v_rcp_f32_e32 v30, v30
	s_nop 0
	v_mul_f32_e32 v30, v33, v30
	v_mul_f32_e32 v29, v30, v29
	v_mul_f32_e32 v30, 0xbfb8aa3b, v22
	v_exp_f32_e32 v30, v30
	s_nop 0
	v_add_f32_e32 v30, 1.0, v30
	v_rcp_f32_e32 v30, v30
	s_nop 0
	v_mul_f32_e32 v22, v22, v30
	v_mul_f32_e32 v30, v22, v18
	v_mul_f32_e32 v18, 0xbfb8aa3b, v23
	v_exp_f32_e32 v18, v18
	s_nop 0
	v_add_f32_e32 v18, 1.0, v18
	v_rcp_f32_e32 v18, v18
	s_nop 0
	v_mul_f32_e32 v18, v23, v18
	v_mul_f32_e32 v31, v18, v19
	v_mul_f32_e32 v18, 0xbfb8aa3b, v24
	v_exp_f32_e32 v18, v18
	v_lshl_add_u64 v[22:23], v[34:35], 0, v[114:115]
	v_add_f32_e32 v18, 1.0, v18
	v_rcp_f32_e32 v18, v18
	s_nop 0
	v_mul_f32_e32 v18, v24, v18
	v_mul_f32_e32 v24, v18, v20
	v_mul_f32_e32 v18, 0xbfb8aa3b, v25
	v_exp_f32_e32 v18, v18
	s_nop 0
	v_add_f32_e32 v18, 1.0, v18
	v_rcp_f32_e32 v18, v18
	s_nop 0
	v_mul_f32_e32 v18, v25, v18
	v_mul_f32_e32 v21, v18, v21
	v_cvt_pk_bf16_f32 v18, v26, v27
	v_cvt_pk_bf16_f32 v19, v28, v29
	v_cvt_pk_bf16_f32 v20, v30, v31
	v_cvt_pk_bf16_f32 v21, v24, v21
	global_store_dwordx4 v[22:23], v[18:21], off
	s_nop 1
	v_mul_f32_e32 v20, 0xbfb8aa3b, v14
	v_exp_f32_e32 v20, v20
	v_add_u32_e32 v18, 0xb0, v144
	v_mad_i64_i32 v[18:19], s[14:15], v18, s72, v[138:139]
	v_add_f32_e32 v20, 1.0, v20
	v_rcp_f32_e32 v20, v20
	s_mov_b64 s[14:15], -1
	v_mul_f32_e32 v14, v14, v20
	v_mul_f32_e32 v10, v14, v10
	v_mul_f32_e32 v14, 0xbfb8aa3b, v15
	v_exp_f32_e32 v14, v14
	s_nop 0
	v_add_f32_e32 v14, 1.0, v14
	v_rcp_f32_e32 v14, v14
	s_nop 0
	v_mul_f32_e32 v14, v15, v14
	v_mul_f32_e32 v11, v14, v11
	v_mul_f32_e32 v14, 0xbfb8aa3b, v16
	v_exp_f32_e32 v14, v14
	s_nop 0
	v_add_f32_e32 v14, 1.0, v14
	v_rcp_f32_e32 v14, v14
	s_nop 0
	v_mul_f32_e32 v14, v16, v14
	v_mul_f32_e32 v12, v14, v12
	v_mul_f32_e32 v14, 0xbfb8aa3b, v17
	v_exp_f32_e32 v14, v14
	s_nop 0
	v_add_f32_e32 v14, 1.0, v14
	v_rcp_f32_e32 v14, v14
	s_nop 0
	v_mul_f32_e32 v14, v17, v14
	v_mul_f32_e32 v13, v14, v13
	v_mul_f32_e32 v14, 0xbfb8aa3b, v6
	v_exp_f32_e32 v14, v14
	s_nop 0
	v_add_f32_e32 v14, 1.0, v14
	v_rcp_f32_e32 v14, v14
	s_nop 0
	v_mul_f32_e32 v6, v6, v14
	v_mul_f32_e32 v14, v6, v2
	v_mul_f32_e32 v2, 0xbfb8aa3b, v7
	v_exp_f32_e32 v2, v2
	s_nop 0
	v_add_f32_e32 v2, 1.0, v2
	v_rcp_f32_e32 v2, v2
	s_nop 0
	v_mul_f32_e32 v2, v7, v2
	v_mul_f32_e32 v15, v2, v3
	v_mul_f32_e32 v2, 0xbfb8aa3b, v8
	v_exp_f32_e32 v2, v2
	v_lshl_add_u64 v[6:7], v[18:19], 0, v[114:115]
	v_add_f32_e32 v2, 1.0, v2
	v_rcp_f32_e32 v2, v2
	s_nop 0
	v_mul_f32_e32 v2, v8, v2
	v_mul_f32_e32 v8, v2, v4
	v_mul_f32_e32 v2, 0xbfb8aa3b, v9
	v_exp_f32_e32 v2, v2
	s_nop 0
	v_add_f32_e32 v2, 1.0, v2
	v_rcp_f32_e32 v2, v2
	s_nop 0
	v_mul_f32_e32 v2, v9, v2
	v_mul_f32_e32 v5, v2, v5
	v_cvt_pk_bf16_f32 v2, v10, v11
	v_cvt_pk_bf16_f32 v3, v12, v13
	v_cvt_pk_bf16_f32 v4, v14, v15
	v_cvt_pk_bf16_f32 v5, v8, v5
	global_store_dwordx4 v[6:7], v[2:5], off
	s_cbranch_vccnz .LBB0_139
	s_andn2_b64 vcc, exec, s[0:1]
	s_cbranch_vccnz .LBB0_138
	s_barrier
	s_branch .LBB0_138

.LBB0_233:
	s_add_u32 s4, s0, 0xfffc0080
	s_addc_u32 s5, s1, -1
	s_add_i32 s18, 0, 0x10000
	s_cmp_eq_u32 s17, 12
	s_cselect_b32 s9, s3, s5
	s_cselect_b32 s8, s11, s4
	v_add_u32_e32 v0, s18, v191
	s_cselect_b32 s5, s12, s15
	s_cselect_b32 s4, s13, s14
	s_add_i32 s25, 0, 0x14000
	ds_read_b128 v[2:5], v0
	ds_read_b128 v[6:9], v0 offset:1024
	ds_read_b128 v[10:13], v0 offset:2048
	ds_read_b128 v[14:17], v0 offset:3072
	v_add_u32_e32 v0, s25, v191
	ds_read_b128 v[146:149], v0
	ds_read_b128 v[150:153], v0 offset:1024
	ds_read_b128 v[154:157], v0 offset:2048
	ds_read_b128 v[158:161], v0 offset:3072
	v_lshl_add_u64 v[230:231], s[0:1], 0, v[178:179]
	s_add_i32 m0, s65, 0xc000
	ds_read_b128 v[162:165], v200
	ds_read_b128 v[166:169], v200 offset:1024
	ds_read_b128 v[182:185], v200 offset:2048
	ds_read_b128 v[186:189], v200 offset:3072
	ds_read_b128 v[202:205], v200 offset:4096
	ds_read_b128 v[206:209], v200 offset:5120
	ds_read_b128 v[222:225], v200 offset:6144
	ds_read_b128 v[226:229], v200 offset:7168
	global_load_lds_dwordx4 v[230:231], off
	v_lshl_add_u64 v[230:231], s[0:1], 0, v[180:181]
	s_add_i32 m0, s65, 0xe000
	s_nop 0
	global_load_lds_dwordx4 v[230:231], off
	s_waitcnt vmcnt(8)
	s_waitcnt lgkmcnt(0)
	s_barrier
	s_setprio 1
	s_waitcnt lgkmcnt(0)
	v_mfma_f32_16x16x32_bf16 v[142:145], v[2:5], v[162:165], v[142:145]
	v_mfma_f32_16x16x32_bf16 v[142:145], v[6:9], v[166:169], v[142:145]
	v_mfma_f32_16x16x32_bf16 v[138:141], v[10:13], v[162:165], v[138:141]
	v_mfma_f32_16x16x32_bf16 v[138:141], v[14:17], v[166:169], v[138:141]
	v_mfma_f32_16x16x32_bf16 v[134:137], v[2:5], v[182:185], v[134:137]
	v_mfma_f32_16x16x32_bf16 v[134:137], v[6:9], v[186:189], v[134:137]
	v_mfma_f32_16x16x32_bf16 v[126:129], v[10:13], v[182:185], v[126:129]
	v_mfma_f32_16x16x32_bf16 v[126:129], v[14:17], v[186:189], v[126:129]
	v_mfma_f32_16x16x32_bf16 v[118:121], v[2:5], v[202:205], v[118:121]
	v_mfma_f32_16x16x32_bf16 v[118:121], v[6:9], v[206:209], v[118:121]
	v_mfma_f32_16x16x32_bf16 v[110:113], v[10:13], v[202:205], v[110:113]
	v_mfma_f32_16x16x32_bf16 v[110:113], v[14:17], v[206:209], v[110:113]
	v_mfma_f32_16x16x32_bf16 v[102:105], v[2:5], v[222:225], v[102:105]
	v_mfma_f32_16x16x32_bf16 v[102:105], v[6:9], v[226:229], v[102:105]
	v_mfma_f32_16x16x32_bf16 v[94:97], v[10:13], v[222:225], v[94:97]
	v_mfma_f32_16x16x32_bf16 v[94:97], v[14:17], v[226:229], v[94:97]
	s_setprio 0
	s_setprio 1
	v_mfma_f32_16x16x32_bf16 v[130:133], v[146:149], v[162:165], v[130:133]
	v_mfma_f32_16x16x32_bf16 v[130:133], v[150:153], v[166:169], v[130:133]
	v_mfma_f32_16x16x32_bf16 v[122:125], v[154:157], v[162:165], v[122:125]
	v_mfma_f32_16x16x32_bf16 v[122:125], v[158:161], v[166:169], v[122:125]
	v_mfma_f32_16x16x32_bf16 v[114:117], v[146:149], v[182:185], v[114:117]
	v_mfma_f32_16x16x32_bf16 v[114:117], v[150:153], v[186:189], v[114:117]
	v_mfma_f32_16x16x32_bf16 v[106:109], v[154:157], v[182:185], v[106:109]
	v_mfma_f32_16x16x32_bf16 v[106:109], v[158:161], v[186:189], v[106:109]
	v_mfma_f32_16x16x32_bf16 v[98:101], v[146:149], v[202:205], v[98:101]
	v_mfma_f32_16x16x32_bf16 v[98:101], v[150:153], v[206:209], v[98:101]
	v_mfma_f32_16x16x32_bf16 v[90:93], v[154:157], v[202:205], v[90:93]
	v_mfma_f32_16x16x32_bf16 v[90:93], v[158:161], v[206:209], v[90:93]
	v_mfma_f32_16x16x32_bf16 v[86:89], v[146:149], v[222:225], v[86:89]
	v_mfma_f32_16x16x32_bf16 v[86:89], v[150:153], v[226:229], v[86:89]
	v_mfma_f32_16x16x32_bf16 v[82:85], v[154:157], v[222:225], v[82:85]
	v_mfma_f32_16x16x32_bf16 v[82:85], v[158:161], v[226:229], v[82:85]
	s_setprio 0
	s_barrier
	s_add_i32 s18, s18, s64
	v_lshl_add_u64 v[230:231], s[4:5], 0, v[172:173]
	s_mov_b32 m0, s18
	ds_read_b128 v[162:165], v200 offset:16384
	ds_read_b128 v[166:169], v200 offset:17408
	ds_read_b128 v[182:185], v200 offset:18432
	ds_read_b128 v[186:189], v200 offset:19456
	ds_read_b128 v[202:205], v200 offset:20480
	ds_read_b128 v[206:209], v200 offset:21504
	ds_read_b128 v[222:225], v200 offset:22528
	ds_read_b128 v[226:229], v200 offset:23552
	global_load_lds_dwordx4 v[230:231], off
	s_add_i32 m0, s18, 0x2000
	s_add_u32 s18, s4, 0x40000
	v_lshl_add_u64 v[232:233], s[4:5], 0, v[170:171]
	s_addc_u32 s19, s5, 0
	s_add_i32 s25, s25, s64
	global_load_lds_dwordx4 v[232:233], off
	v_lshl_add_u64 v[246:247], s[18:19], 0, v[172:173]
	s_mov_b32 m0, s25
	v_lshl_add_u64 v[248:249], s[8:9], 0, v[170:171]
	global_load_lds_dwordx4 v[246:247], off
	v_lshl_add_u64 v[246:247], s[18:19], 0, v[170:171]
	s_add_i32 m0, s25, 0x2000
	s_nop 0
	global_load_lds_dwordx4 v[246:247], off
	v_lshl_add_u64 v[246:247], s[8:9], 0, v[172:173]
	s_mov_b32 m0, s65
	s_nop 0
	global_load_lds_dwordx4 v[246:247], off
	s_mov_b32 m0, s68
	s_nop 0
	global_load_lds_dwordx4 v[248:249], off
	s_waitcnt vmcnt(8)
	s_waitcnt lgkmcnt(0)
	s_barrier
	s_setprio 1
	s_waitcnt lgkmcnt(0)
	v_mfma_f32_16x16x32_bf16 v[78:81], v[2:5], v[162:165], v[78:81]
	v_mfma_f32_16x16x32_bf16 v[74:77], v[10:13], v[162:165], v[74:77]
	v_mfma_f32_16x16x32_bf16 v[70:73], v[2:5], v[182:185], v[70:73]
	v_mfma_f32_16x16x32_bf16 v[62:65], v[10:13], v[182:185], v[62:65]
	v_mfma_f32_16x16x32_bf16 v[54:57], v[2:5], v[202:205], v[54:57]
	v_mfma_f32_16x16x32_bf16 v[46:49], v[10:13], v[202:205], v[46:49]
	v_mfma_f32_16x16x32_bf16 v[2:5], v[2:5], v[222:225], v[38:41]
	v_mfma_f32_16x16x32_bf16 v[78:81], v[6:9], v[166:169], v[78:81]
	v_mfma_f32_16x16x32_bf16 v[74:77], v[14:17], v[166:169], v[74:77]
	v_mfma_f32_16x16x32_bf16 v[70:73], v[6:9], v[186:189], v[70:73]
	v_mfma_f32_16x16x32_bf16 v[62:65], v[14:17], v[186:189], v[62:65]
	v_mfma_f32_16x16x32_bf16 v[54:57], v[6:9], v[206:209], v[54:57]
	v_mfma_f32_16x16x32_bf16 v[46:49], v[14:17], v[206:209], v[46:49]
	v_mfma_f32_16x16x32_bf16 v[2:5], v[6:9], v[226:229], v[2:5]
	v_mfma_f32_16x16x32_bf16 v[6:9], v[10:13], v[222:225], v[30:33]
	v_mfma_f32_16x16x32_bf16 v[6:9], v[14:17], v[226:229], v[6:9]
	s_setprio 0
	s_setprio 1
	v_mfma_f32_16x16x32_bf16 v[30:33], v[146:149], v[182:185], v[50:53]
	v_mfma_f32_16x16x32_bf16 v[50:53], v[150:153], v[186:189], v[30:33]
	v_mfma_f32_16x16x32_bf16 v[30:33], v[154:157], v[182:185], v[42:45]
	v_mfma_f32_16x16x32_bf16 v[42:45], v[158:161], v[186:189], v[30:33]
	v_mfma_f32_16x16x32_bf16 v[30:33], v[146:149], v[202:205], v[34:37]
	v_mfma_f32_16x16x32_bf16 v[26:29], v[154:157], v[202:205], v[26:29]
	v_mfma_f32_16x16x32_bf16 v[22:25], v[146:149], v[222:225], v[22:25]
	v_mfma_f32_16x16x32_bf16 v[18:21], v[154:157], v[222:225], v[18:21]
	v_mfma_f32_16x16x32_bf16 v[10:13], v[146:149], v[162:165], v[66:69]
	v_mfma_f32_16x16x32_bf16 v[14:17], v[154:157], v[162:165], v[58:61]
	v_mfma_f32_16x16x32_bf16 v[34:37], v[150:153], v[206:209], v[30:33]
	v_mfma_f32_16x16x32_bf16 v[26:29], v[158:161], v[206:209], v[26:29]
	v_mfma_f32_16x16x32_bf16 v[22:25], v[150:153], v[226:229], v[22:25]
	v_mfma_f32_16x16x32_bf16 v[18:21], v[158:161], v[226:229], v[18:21]
	v_mfma_f32_16x16x32_bf16 v[10:13], v[150:153], v[166:169], v[10:13]
	v_mfma_f32_16x16x32_bf16 v[14:17], v[158:161], v[166:169], v[14:17]
	s_setprio 0
	s_barrier
	s_add_i32 s18, 0, 0x18000
	v_add_u32_e32 v0, s18, v191
	s_add_i32 s19, 0, 0x1c000
	ds_read_b128 v[30:33], v0
	ds_read_b128 v[38:41], v0 offset:1024
	ds_read_b128 v[58:61], v0 offset:2048
	ds_read_b128 v[66:69], v0 offset:3072
	v_add_u32_e32 v0, s19, v191
	ds_read_b128 v[146:149], v0
	ds_read_b128 v[150:153], v0 offset:1024
	ds_read_b128 v[154:157], v0 offset:2048
	ds_read_b128 v[158:161], v0 offset:3072
	s_add_u32 s8, s8, 0x40000
	s_addc_u32 s9, s9, 0
	s_mov_b32 m0, s69
	v_lshl_add_u64 v[250:251], s[8:9], 0, v[172:173]
	ds_read_b128 v[162:165], v200 offset:32768
	ds_read_b128 v[166:169], v200 offset:33792
	ds_read_b128 v[182:185], v200 offset:34816
	ds_read_b128 v[186:189], v200 offset:35840
	ds_read_b128 v[202:205], v200 offset:36864
	ds_read_b128 v[206:209], v200 offset:37888
	ds_read_b128 v[222:225], v200 offset:38912
	ds_read_b128 v[226:229], v200 offset:39936
	global_load_lds_dwordx4 v[250:251], off
	v_lshl_add_u64 v[250:251], s[8:9], 0, v[170:171]
	s_mov_b32 m0, s70
	s_nop 0
	global_load_lds_dwordx4 v[250:251], off
	s_waitcnt vmcnt(8)
	s_waitcnt lgkmcnt(0)
	s_barrier
	s_setprio 1
	s_waitcnt lgkmcnt(0)
	v_mfma_f32_16x16x32_bf16 v[142:145], v[30:33], v[162:165], v[142:145]
	v_mfma_f32_16x16x32_bf16 v[142:145], v[38:41], v[166:169], v[142:145]
	v_mfma_f32_16x16x32_bf16 v[138:141], v[58:61], v[162:165], v[138:141]
	v_mfma_f32_16x16x32_bf16 v[138:141], v[66:69], v[166:169], v[138:141]
	v_mfma_f32_16x16x32_bf16 v[134:137], v[30:33], v[182:185], v[134:137]
	v_mfma_f32_16x16x32_bf16 v[134:137], v[38:41], v[186:189], v[134:137]
	v_mfma_f32_16x16x32_bf16 v[126:129], v[58:61], v[182:185], v[126:129]
	v_mfma_f32_16x16x32_bf16 v[126:129], v[66:69], v[186:189], v[126:129]
	v_mfma_f32_16x16x32_bf16 v[118:121], v[30:33], v[202:205], v[118:121]
	v_mfma_f32_16x16x32_bf16 v[118:121], v[38:41], v[206:209], v[118:121]
	v_mfma_f32_16x16x32_bf16 v[110:113], v[58:61], v[202:205], v[110:113]
	v_mfma_f32_16x16x32_bf16 v[110:113], v[66:69], v[206:209], v[110:113]
	v_mfma_f32_16x16x32_bf16 v[102:105], v[30:33], v[222:225], v[102:105]
	v_mfma_f32_16x16x32_bf16 v[102:105], v[38:41], v[226:229], v[102:105]
	v_mfma_f32_16x16x32_bf16 v[94:97], v[58:61], v[222:225], v[94:97]
	v_mfma_f32_16x16x32_bf16 v[94:97], v[66:69], v[226:229], v[94:97]
	s_setprio 0
	s_setprio 1
	v_mfma_f32_16x16x32_bf16 v[130:133], v[146:149], v[162:165], v[130:133]
	v_mfma_f32_16x16x32_bf16 v[130:133], v[150:153], v[166:169], v[130:133]
	v_mfma_f32_16x16x32_bf16 v[122:125], v[154:157], v[162:165], v[122:125]
	v_mfma_f32_16x16x32_bf16 v[122:125], v[158:161], v[166:169], v[122:125]
	v_mfma_f32_16x16x32_bf16 v[114:117], v[146:149], v[182:185], v[114:117]
	v_mfma_f32_16x16x32_bf16 v[114:117], v[150:153], v[186:189], v[114:117]
	v_mfma_f32_16x16x32_bf16 v[106:109], v[154:157], v[182:185], v[106:109]
	v_mfma_f32_16x16x32_bf16 v[106:109], v[158:161], v[186:189], v[106:109]
	v_mfma_f32_16x16x32_bf16 v[98:101], v[146:149], v[202:205], v[98:101]
	v_mfma_f32_16x16x32_bf16 v[98:101], v[150:153], v[206:209], v[98:101]
	v_mfma_f32_16x16x32_bf16 v[90:93], v[154:157], v[202:205], v[90:93]
	v_mfma_f32_16x16x32_bf16 v[90:93], v[158:161], v[206:209], v[90:93]
	v_mfma_f32_16x16x32_bf16 v[86:89], v[146:149], v[222:225], v[86:89]
	v_mfma_f32_16x16x32_bf16 v[86:89], v[150:153], v[226:229], v[86:89]
	v_mfma_f32_16x16x32_bf16 v[82:85], v[154:157], v[222:225], v[82:85]
	v_mfma_f32_16x16x32_bf16 v[82:85], v[158:161], v[226:229], v[82:85]
	s_setprio 0
	s_barrier
	s_add_i32 s8, s18, s64
	v_lshl_add_u64 v[230:231], v[230:231], 0, s[22:23]
	s_mov_b32 m0, s8
	ds_read_b128 v[162:165], v200 offset:49152
	ds_read_b128 v[166:169], v200 offset:50176
	ds_read_b128 v[182:185], v200 offset:51200
	ds_read_b128 v[186:189], v200 offset:52224
	ds_read_b128 v[202:205], v200 offset:53248
	ds_read_b128 v[206:209], v200 offset:54272
	ds_read_b128 v[222:225], v200 offset:55296
	ds_read_b128 v[226:229], v200 offset:56320
	global_load_lds_dwordx4 v[230:231], off
	s_add_i32 m0, s8, 0x2000
	s_add_u32 s4, s4, 0x40080
	v_lshl_add_u64 v[230:231], v[232:233], 0, s[22:23]
	s_addc_u32 s5, s5, 0
	s_add_i32 s8, s19, s64
	global_load_lds_dwordx4 v[230:231], off
	v_lshl_add_u64 v[230:231], s[4:5], 0, v[172:173]
	s_mov_b32 m0, s8
	s_nop 0
	global_load_lds_dwordx4 v[230:231], off
	v_lshl_add_u64 v[230:231], s[4:5], 0, v[170:171]
	s_add_i32 m0, s8, 0x2000
	s_nop 0
	global_load_lds_dwordx4 v[230:231], off
	v_lshl_add_u64 v[230:231], v[246:247], 0, s[22:23]
	s_mov_b32 m0, s94
	s_nop 0
	global_load_lds_dwordx4 v[230:231], off
	v_lshl_add_u64 v[230:231], v[248:249], 0, s[22:23]
	s_mov_b32 m0, s95
	s_nop 0
	global_load_lds_dwordx4 v[230:231], off
	s_waitcnt vmcnt(8)
	s_waitcnt lgkmcnt(0)
	s_barrier
	s_setprio 1
	s_waitcnt lgkmcnt(0)
	v_mfma_f32_16x16x32_bf16 v[78:81], v[30:33], v[162:165], v[78:81]
	v_mfma_f32_16x16x32_bf16 v[70:73], v[30:33], v[182:185], v[70:73]
	v_mfma_f32_16x16x32_bf16 v[54:57], v[30:33], v[202:205], v[54:57]
	v_mfma_f32_16x16x32_bf16 v[2:5], v[30:33], v[222:225], v[2:5]
	v_mfma_f32_16x16x32_bf16 v[78:81], v[38:41], v[166:169], v[78:81]
	v_mfma_f32_16x16x32_bf16 v[74:77], v[58:61], v[162:165], v[74:77]
	v_mfma_f32_16x16x32_bf16 v[70:73], v[38:41], v[186:189], v[70:73]
	v_mfma_f32_16x16x32_bf16 v[62:65], v[58:61], v[182:185], v[62:65]
	v_mfma_f32_16x16x32_bf16 v[54:57], v[38:41], v[206:209], v[54:57]
	v_mfma_f32_16x16x32_bf16 v[46:49], v[58:61], v[202:205], v[46:49]
	v_mfma_f32_16x16x32_bf16 v[38:41], v[38:41], v[226:229], v[2:5]
	v_mfma_f32_16x16x32_bf16 v[2:5], v[58:61], v[222:225], v[6:9]
	v_mfma_f32_16x16x32_bf16 v[74:77], v[66:69], v[166:169], v[74:77]
	v_mfma_f32_16x16x32_bf16 v[62:65], v[66:69], v[186:189], v[62:65]
	v_mfma_f32_16x16x32_bf16 v[46:49], v[66:69], v[206:209], v[46:49]
	v_mfma_f32_16x16x32_bf16 v[30:33], v[66:69], v[226:229], v[2:5]
	s_setprio 0
	s_setprio 1
	v_mfma_f32_16x16x32_bf16 v[2:5], v[146:149], v[162:165], v[10:13]
	v_mfma_f32_16x16x32_bf16 v[66:69], v[150:153], v[166:169], v[2:5]
	v_mfma_f32_16x16x32_bf16 v[2:5], v[154:157], v[162:165], v[14:17]
	v_mfma_f32_16x16x32_bf16 v[58:61], v[158:161], v[166:169], v[2:5]
	v_mfma_f32_16x16x32_bf16 v[2:5], v[146:149], v[182:185], v[50:53]
	v_mfma_f32_16x16x32_bf16 v[50:53], v[150:153], v[186:189], v[2:5]
	v_mfma_f32_16x16x32_bf16 v[2:5], v[154:157], v[182:185], v[42:45]
	v_mfma_f32_16x16x32_bf16 v[42:45], v[158:161], v[186:189], v[2:5]
	v_mfma_f32_16x16x32_bf16 v[2:5], v[146:149], v[202:205], v[34:37]
	v_mfma_f32_16x16x32_bf16 v[34:37], v[150:153], v[206:209], v[2:5]
	v_mfma_f32_16x16x32_bf16 v[2:5], v[154:157], v[202:205], v[26:29]
	v_mfma_f32_16x16x32_bf16 v[26:29], v[158:161], v[206:209], v[2:5]
	v_mfma_f32_16x16x32_bf16 v[2:5], v[146:149], v[222:225], v[22:25]
	v_mfma_f32_16x16x32_bf16 v[22:25], v[150:153], v[226:229], v[2:5]
	v_mfma_f32_16x16x32_bf16 v[2:5], v[154:157], v[222:225], v[18:21]
	v_mfma_f32_16x16x32_bf16 v[18:21], v[158:161], v[226:229], v[2:5]
	s_setprio 0
	s_barrier
	s_add_i32 s17, s17, 2
	s_add_u32 s0, s0, 0x100
	s_addc_u32 s1, s1, 0
	s_add_u32 s14, s14, 0x100
	s_addc_u32 s15, s15, 0
	s_cmp_gt_u32 s17, 13
	s_cbranch_scc0 .LBB0_233
	s_and_b64 vcc, exec, s[78:79]
	s_cbranch_vccz .LBB0_236
	s_barrier

.LBB0_707:
	s_add_i32 s34, s68, 2
	s_add_u32 s35, s0, 0x80
	s_addc_u32 s69, s1, 0
	s_add_i32 s84, 0, 0x10000
	s_cmp_eq_u32 s96, s68
	s_cselect_b32 s69, s53, s69
	s_cselect_b32 s68, s52, s35
	s_cselect_b32 s89, s65, vcc_hi
	s_cselect_b32 s88, s64, vcc_lo
	s_add_i32 s35, 0, 0x14000
	v_add_u32_e32 v142, s84, v212
	v_add_u32_e32 v158, s35, v212
	ds_read_b128 v[130:133], v142
	ds_read_b128 v[134:137], v142 offset:1024
	ds_read_b128 v[138:141], v142 offset:2048
	ds_read_b128 v[142:145], v142 offset:3072
	ds_read_b128 v[146:149], v158
	ds_read_b128 v[150:153], v158 offset:1024
	ds_read_b128 v[154:157], v158 offset:2048
	ds_read_b128 v[158:161], v158 offset:3072
	v_lshl_add_u64 v[194:195], s[0:1], 0, v[224:225]
	s_add_i32 m0, s28, 0xc000
	ds_read_b128 v[162:165], v245
	ds_read_b128 v[166:169], v245 offset:1024
	ds_read_b128 v[170:173], v245 offset:2048
	ds_read_b128 v[174:177], v245 offset:3072
	ds_read_b128 v[178:181], v245 offset:4096
	ds_read_b128 v[182:185], v245 offset:5120
	ds_read_b128 v[186:189], v245 offset:6144
	ds_read_b128 v[190:193], v245 offset:7168
	global_load_lds_dwordx4 v[194:195], off
	v_lshl_add_u64 v[194:195], s[0:1], 0, v[226:227]
	s_add_i32 m0, s28, 0xe000
	s_nop 0
	global_load_lds_dwordx4 v[194:195], off
	s_waitcnt vmcnt(8)
	s_waitcnt lgkmcnt(0)
	s_barrier
	s_setprio 1
	s_waitcnt lgkmcnt(0)
	v_mfma_f32_16x16x32_bf16 v[126:129], v[130:133], v[162:165], v[126:129]
	v_mfma_f32_16x16x32_bf16 v[126:129], v[134:137], v[166:169], v[126:129]
	v_mfma_f32_16x16x32_bf16 v[122:125], v[138:141], v[162:165], v[122:125]
	v_mfma_f32_16x16x32_bf16 v[122:125], v[142:145], v[166:169], v[122:125]
	v_mfma_f32_16x16x32_bf16 v[114:117], v[130:133], v[170:173], v[114:117]
	v_mfma_f32_16x16x32_bf16 v[114:117], v[134:137], v[174:177], v[114:117]
	v_mfma_f32_16x16x32_bf16 v[106:109], v[138:141], v[170:173], v[106:109]
	v_mfma_f32_16x16x32_bf16 v[106:109], v[142:145], v[174:177], v[106:109]
	v_mfma_f32_16x16x32_bf16 v[98:101], v[130:133], v[178:181], v[98:101]
	v_mfma_f32_16x16x32_bf16 v[98:101], v[134:137], v[182:185], v[98:101]
	v_mfma_f32_16x16x32_bf16 v[90:93], v[138:141], v[178:181], v[90:93]
	v_mfma_f32_16x16x32_bf16 v[90:93], v[142:145], v[182:185], v[90:93]
	v_mfma_f32_16x16x32_bf16 v[82:85], v[130:133], v[186:189], v[82:85]
	v_mfma_f32_16x16x32_bf16 v[82:85], v[134:137], v[190:193], v[82:85]
	v_mfma_f32_16x16x32_bf16 v[74:77], v[138:141], v[186:189], v[74:77]
	v_mfma_f32_16x16x32_bf16 v[74:77], v[142:145], v[190:193], v[74:77]
	s_setprio 0
	s_setprio 1
	v_mfma_f32_16x16x32_bf16 v[118:121], v[146:149], v[162:165], v[118:121]
	v_mfma_f32_16x16x32_bf16 v[118:121], v[150:153], v[166:169], v[118:121]
	v_mfma_f32_16x16x32_bf16 v[110:113], v[154:157], v[162:165], v[110:113]
	v_mfma_f32_16x16x32_bf16 v[110:113], v[158:161], v[166:169], v[110:113]
	v_mfma_f32_16x16x32_bf16 v[102:105], v[146:149], v[170:173], v[102:105]
	v_mfma_f32_16x16x32_bf16 v[102:105], v[150:153], v[174:177], v[102:105]
	v_mfma_f32_16x16x32_bf16 v[94:97], v[154:157], v[170:173], v[94:97]
	v_mfma_f32_16x16x32_bf16 v[94:97], v[158:161], v[174:177], v[94:97]
	v_mfma_f32_16x16x32_bf16 v[86:89], v[146:149], v[178:181], v[86:89]
	v_mfma_f32_16x16x32_bf16 v[86:89], v[150:153], v[182:185], v[86:89]
	v_mfma_f32_16x16x32_bf16 v[78:81], v[154:157], v[178:181], v[78:81]
	v_mfma_f32_16x16x32_bf16 v[78:81], v[158:161], v[182:185], v[78:81]
	v_mfma_f32_16x16x32_bf16 v[70:73], v[146:149], v[186:189], v[70:73]
	v_mfma_f32_16x16x32_bf16 v[70:73], v[150:153], v[190:193], v[70:73]
	v_mfma_f32_16x16x32_bf16 v[66:69], v[154:157], v[186:189], v[66:69]
	v_mfma_f32_16x16x32_bf16 v[66:69], v[158:161], v[190:193], v[66:69]
	s_setprio 0
	s_barrier
	s_add_i32 s84, s84, s19
	v_lshl_add_u64 v[194:195], s[88:89], 0, v[0:1]
	s_mov_b32 m0, s84
	ds_read_b128 v[162:165], v245 offset:16384
	ds_read_b128 v[166:169], v245 offset:17408
	ds_read_b128 v[170:173], v245 offset:18432
	ds_read_b128 v[174:177], v245 offset:19456
	ds_read_b128 v[178:181], v245 offset:20480
	ds_read_b128 v[182:185], v245 offset:21504
	ds_read_b128 v[186:189], v245 offset:22528
	ds_read_b128 v[190:193], v245 offset:23552
	global_load_lds_dwordx4 v[194:195], off
	s_add_i32 m0, s84, 0x2000
	v_lshl_add_u64 v[196:197], s[88:89], 0, v[222:223]
	s_add_u32 s88, s88, s2
	s_addc_u32 s89, s89, 0
	s_add_i32 s35, s35, s19
	global_load_lds_dwordx4 v[196:197], off
	v_lshl_add_u64 v[198:199], s[88:89], 0, v[0:1]
	s_mov_b32 m0, s35
	v_lshl_add_u64 v[200:201], s[88:89], 0, v[222:223]
	global_load_lds_dwordx4 v[198:199], off
	s_add_i32 m0, s35, 0x2000
	v_lshl_add_u64 v[202:203], s[68:69], 0, v[0:1]
	global_load_lds_dwordx4 v[200:201], off
	s_mov_b32 m0, s28
	v_lshl_add_u64 v[204:205], s[68:69], 0, v[222:223]
	global_load_lds_dwordx4 v[202:203], off
	s_mov_b32 m0, s29
	s_nop 0
	global_load_lds_dwordx4 v[204:205], off
	s_waitcnt vmcnt(8)
	s_waitcnt lgkmcnt(0)
	s_barrier
	s_setprio 1
	s_waitcnt lgkmcnt(0)
	v_mfma_f32_16x16x32_bf16 v[62:65], v[130:133], v[162:165], v[62:65]
	v_mfma_f32_16x16x32_bf16 v[62:65], v[134:137], v[166:169], v[62:65]
	v_mfma_f32_16x16x32_bf16 v[58:61], v[138:141], v[162:165], v[58:61]
	v_mfma_f32_16x16x32_bf16 v[58:61], v[142:145], v[166:169], v[58:61]
	v_mfma_f32_16x16x32_bf16 v[50:53], v[130:133], v[170:173], v[50:53]
	v_mfma_f32_16x16x32_bf16 v[50:53], v[134:137], v[174:177], v[50:53]
	v_mfma_f32_16x16x32_bf16 v[42:45], v[138:141], v[170:173], v[42:45]
	v_mfma_f32_16x16x32_bf16 v[42:45], v[142:145], v[174:177], v[42:45]
	v_mfma_f32_16x16x32_bf16 v[34:37], v[130:133], v[178:181], v[34:37]
	v_mfma_f32_16x16x32_bf16 v[34:37], v[134:137], v[182:185], v[34:37]
	v_mfma_f32_16x16x32_bf16 v[26:29], v[138:141], v[178:181], v[26:29]
	v_mfma_f32_16x16x32_bf16 v[26:29], v[142:145], v[182:185], v[26:29]
	v_mfma_f32_16x16x32_bf16 v[18:21], v[130:133], v[186:189], v[18:21]
	v_mfma_f32_16x16x32_bf16 v[18:21], v[134:137], v[190:193], v[18:21]
	v_mfma_f32_16x16x32_bf16 v[10:13], v[138:141], v[186:189], v[10:13]
	v_mfma_f32_16x16x32_bf16 v[10:13], v[142:145], v[190:193], v[10:13]
	s_setprio 0
	s_setprio 1
	v_mfma_f32_16x16x32_bf16 v[54:57], v[146:149], v[162:165], v[54:57]
	v_mfma_f32_16x16x32_bf16 v[54:57], v[150:153], v[166:169], v[54:57]
	v_mfma_f32_16x16x32_bf16 v[46:49], v[154:157], v[162:165], v[46:49]
	v_mfma_f32_16x16x32_bf16 v[46:49], v[158:161], v[166:169], v[46:49]
	v_mfma_f32_16x16x32_bf16 v[38:41], v[146:149], v[170:173], v[38:41]
	v_mfma_f32_16x16x32_bf16 v[38:41], v[150:153], v[174:177], v[38:41]
	v_mfma_f32_16x16x32_bf16 v[30:33], v[154:157], v[170:173], v[30:33]
	v_mfma_f32_16x16x32_bf16 v[30:33], v[158:161], v[174:177], v[30:33]
	v_mfma_f32_16x16x32_bf16 v[22:25], v[146:149], v[178:181], v[22:25]
	v_mfma_f32_16x16x32_bf16 v[22:25], v[150:153], v[182:185], v[22:25]
	v_mfma_f32_16x16x32_bf16 v[14:17], v[154:157], v[178:181], v[14:17]
	v_mfma_f32_16x16x32_bf16 v[14:17], v[158:161], v[182:185], v[14:17]
	v_mfma_f32_16x16x32_bf16 v[6:9], v[146:149], v[186:189], v[6:9]
	v_mfma_f32_16x16x32_bf16 v[6:9], v[150:153], v[190:193], v[6:9]
	v_mfma_f32_16x16x32_bf16 v[2:5], v[154:157], v[186:189], v[2:5]
	v_mfma_f32_16x16x32_bf16 v[2:5], v[158:161], v[190:193], v[2:5]
	s_setprio 0
	s_barrier
	s_add_i32 s35, 0, 0x18000
	s_add_i32 s84, 0, 0x1c000
	v_add_u32_e32 v142, s35, v212
	v_add_u32_e32 v158, s84, v212
	ds_read_b128 v[130:133], v142
	ds_read_b128 v[134:137], v142 offset:1024
	ds_read_b128 v[138:141], v142 offset:2048
	ds_read_b128 v[142:145], v142 offset:3072
	ds_read_b128 v[146:149], v158
	ds_read_b128 v[150:153], v158 offset:1024
	ds_read_b128 v[154:157], v158 offset:2048
	ds_read_b128 v[158:161], v158 offset:3072
	s_add_u32 s68, s68, s2
	s_addc_u32 s69, s69, 0
	s_mov_b32 m0, s25
	v_lshl_add_u64 v[206:207], s[68:69], 0, v[0:1]
	ds_read_b128 v[162:165], v245 offset:32768
	ds_read_b128 v[166:169], v245 offset:33792
	ds_read_b128 v[170:173], v245 offset:34816
	ds_read_b128 v[174:177], v245 offset:35840
	ds_read_b128 v[178:181], v245 offset:36864
	ds_read_b128 v[182:185], v245 offset:37888
	ds_read_b128 v[186:189], v245 offset:38912
	ds_read_b128 v[190:193], v245 offset:39936
	global_load_lds_dwordx4 v[206:207], off
	v_lshl_add_u64 v[206:207], s[68:69], 0, v[222:223]
	s_mov_b32 m0, s36
	s_nop 0
	global_load_lds_dwordx4 v[206:207], off
	s_waitcnt vmcnt(8)
	s_waitcnt lgkmcnt(0)
	s_barrier
	s_setprio 1
	s_waitcnt lgkmcnt(0)
	v_mfma_f32_16x16x32_bf16 v[126:129], v[130:133], v[162:165], v[126:129]
	v_mfma_f32_16x16x32_bf16 v[126:129], v[134:137], v[166:169], v[126:129]
	v_mfma_f32_16x16x32_bf16 v[122:125], v[138:141], v[162:165], v[122:125]
	v_mfma_f32_16x16x32_bf16 v[122:125], v[142:145], v[166:169], v[122:125]
	v_mfma_f32_16x16x32_bf16 v[114:117], v[130:133], v[170:173], v[114:117]
	v_mfma_f32_16x16x32_bf16 v[114:117], v[134:137], v[174:177], v[114:117]
	v_mfma_f32_16x16x32_bf16 v[106:109], v[138:141], v[170:173], v[106:109]
	v_mfma_f32_16x16x32_bf16 v[106:109], v[142:145], v[174:177], v[106:109]
	v_mfma_f32_16x16x32_bf16 v[98:101], v[130:133], v[178:181], v[98:101]
	v_mfma_f32_16x16x32_bf16 v[98:101], v[134:137], v[182:185], v[98:101]
	v_mfma_f32_16x16x32_bf16 v[90:93], v[138:141], v[178:181], v[90:93]
	v_mfma_f32_16x16x32_bf16 v[90:93], v[142:145], v[182:185], v[90:93]
	v_mfma_f32_16x16x32_bf16 v[82:85], v[130:133], v[186:189], v[82:85]
	v_mfma_f32_16x16x32_bf16 v[82:85], v[134:137], v[190:193], v[82:85]
	v_mfma_f32_16x16x32_bf16 v[74:77], v[138:141], v[186:189], v[74:77]
	v_mfma_f32_16x16x32_bf16 v[74:77], v[142:145], v[190:193], v[74:77]
	s_setprio 0
	s_setprio 1
	v_mfma_f32_16x16x32_bf16 v[118:121], v[146:149], v[162:165], v[118:121]
	v_mfma_f32_16x16x32_bf16 v[118:121], v[150:153], v[166:169], v[118:121]
	v_mfma_f32_16x16x32_bf16 v[110:113], v[154:157], v[162:165], v[110:113]
	v_mfma_f32_16x16x32_bf16 v[110:113], v[158:161], v[166:169], v[110:113]
	v_mfma_f32_16x16x32_bf16 v[102:105], v[146:149], v[170:173], v[102:105]
	v_mfma_f32_16x16x32_bf16 v[102:105], v[150:153], v[174:177], v[102:105]
	v_mfma_f32_16x16x32_bf16 v[94:97], v[154:157], v[170:173], v[94:97]
	v_mfma_f32_16x16x32_bf16 v[94:97], v[158:161], v[174:177], v[94:97]
	v_mfma_f32_16x16x32_bf16 v[86:89], v[146:149], v[178:181], v[86:89]
	v_mfma_f32_16x16x32_bf16 v[86:89], v[150:153], v[182:185], v[86:89]
	v_mfma_f32_16x16x32_bf16 v[78:81], v[154:157], v[178:181], v[78:81]
	v_mfma_f32_16x16x32_bf16 v[78:81], v[158:161], v[182:185], v[78:81]
	v_mfma_f32_16x16x32_bf16 v[70:73], v[146:149], v[186:189], v[70:73]
	v_mfma_f32_16x16x32_bf16 v[70:73], v[150:153], v[190:193], v[70:73]
	v_mfma_f32_16x16x32_bf16 v[66:69], v[154:157], v[186:189], v[66:69]
	v_mfma_f32_16x16x32_bf16 v[66:69], v[158:161], v[190:193], v[66:69]
	s_setprio 0
	s_barrier
	s_add_i32 s35, s35, s19
	v_lshl_add_u64 v[194:195], v[194:195], 0, s[22:23]
	s_mov_b32 m0, s35
	ds_read_b128 v[162:165], v245 offset:49152
	ds_read_b128 v[166:169], v245 offset:50176
	ds_read_b128 v[170:173], v245 offset:51200
	ds_read_b128 v[174:177], v245 offset:52224
	ds_read_b128 v[178:181], v245 offset:53248
	ds_read_b128 v[182:185], v245 offset:54272
	ds_read_b128 v[186:189], v245 offset:55296
	ds_read_b128 v[190:193], v245 offset:56320
	global_load_lds_dwordx4 v[194:195], off
	v_lshl_add_u64 v[194:195], v[196:197], 0, s[22:23]
	s_add_i32 m0, s35, 0x2000
	s_add_i32 s35, s84, s19
	global_load_lds_dwordx4 v[194:195], off
	v_lshl_add_u64 v[194:195], v[198:199], 0, s[22:23]
	s_mov_b32 m0, s35
	s_nop 0
	global_load_lds_dwordx4 v[194:195], off
	v_lshl_add_u64 v[194:195], v[200:201], 0, s[22:23]
	s_add_i32 m0, s35, 0x2000
	s_nop 0
	global_load_lds_dwordx4 v[194:195], off
	v_lshl_add_u64 v[194:195], v[202:203], 0, s[22:23]
	s_mov_b32 m0, s37
	s_nop 0
	global_load_lds_dwordx4 v[194:195], off
	v_lshl_add_u64 v[194:195], v[204:205], 0, s[22:23]
	s_mov_b32 m0, s40
	s_nop 0
	global_load_lds_dwordx4 v[194:195], off
	s_waitcnt vmcnt(8)
	s_waitcnt lgkmcnt(0)
	s_barrier
	s_setprio 1
	s_waitcnt lgkmcnt(0)
	v_mfma_f32_16x16x32_bf16 v[62:65], v[130:133], v[162:165], v[62:65]
	v_mfma_f32_16x16x32_bf16 v[62:65], v[134:137], v[166:169], v[62:65]
	v_mfma_f32_16x16x32_bf16 v[58:61], v[138:141], v[162:165], v[58:61]
	v_mfma_f32_16x16x32_bf16 v[58:61], v[142:145], v[166:169], v[58:61]
	v_mfma_f32_16x16x32_bf16 v[50:53], v[130:133], v[170:173], v[50:53]
	v_mfma_f32_16x16x32_bf16 v[50:53], v[134:137], v[174:177], v[50:53]
	v_mfma_f32_16x16x32_bf16 v[42:45], v[138:141], v[170:173], v[42:45]
	v_mfma_f32_16x16x32_bf16 v[42:45], v[142:145], v[174:177], v[42:45]
	v_mfma_f32_16x16x32_bf16 v[34:37], v[130:133], v[178:181], v[34:37]
	v_mfma_f32_16x16x32_bf16 v[34:37], v[134:137], v[182:185], v[34:37]
	v_mfma_f32_16x16x32_bf16 v[26:29], v[138:141], v[178:181], v[26:29]
	v_mfma_f32_16x16x32_bf16 v[26:29], v[142:145], v[182:185], v[26:29]
	v_mfma_f32_16x16x32_bf16 v[18:21], v[130:133], v[186:189], v[18:21]
	v_mfma_f32_16x16x32_bf16 v[18:21], v[134:137], v[190:193], v[18:21]
	v_mfma_f32_16x16x32_bf16 v[10:13], v[138:141], v[186:189], v[10:13]
	v_mfma_f32_16x16x32_bf16 v[10:13], v[142:145], v[190:193], v[10:13]
	s_setprio 0
	s_setprio 1
	v_mfma_f32_16x16x32_bf16 v[54:57], v[146:149], v[162:165], v[54:57]
	v_mfma_f32_16x16x32_bf16 v[54:57], v[150:153], v[166:169], v[54:57]
	v_mfma_f32_16x16x32_bf16 v[46:49], v[154:157], v[162:165], v[46:49]
	v_mfma_f32_16x16x32_bf16 v[46:49], v[158:161], v[166:169], v[46:49]
	v_mfma_f32_16x16x32_bf16 v[38:41], v[146:149], v[170:173], v[38:41]
	v_mfma_f32_16x16x32_bf16 v[38:41], v[150:153], v[174:177], v[38:41]
	v_mfma_f32_16x16x32_bf16 v[30:33], v[154:157], v[170:173], v[30:33]
	v_mfma_f32_16x16x32_bf16 v[30:33], v[158:161], v[174:177], v[30:33]
	v_mfma_f32_16x16x32_bf16 v[22:25], v[146:149], v[178:181], v[22:25]
	v_mfma_f32_16x16x32_bf16 v[22:25], v[150:153], v[182:185], v[22:25]
	v_mfma_f32_16x16x32_bf16 v[14:17], v[154:157], v[178:181], v[14:17]
	v_mfma_f32_16x16x32_bf16 v[14:17], v[158:161], v[182:185], v[14:17]
	v_mfma_f32_16x16x32_bf16 v[6:9], v[146:149], v[186:189], v[6:9]
	v_mfma_f32_16x16x32_bf16 v[6:9], v[150:153], v[190:193], v[6:9]
	v_mfma_f32_16x16x32_bf16 v[2:5], v[154:157], v[186:189], v[2:5]
	v_mfma_f32_16x16x32_bf16 v[2:5], v[158:161], v[190:193], v[2:5]
	s_setprio 0
	s_barrier
	s_add_u32 s0, s0, 0x100
	s_addc_u32 s1, s1, 0
	s_add_u32 vcc_lo, vcc_lo, 0x100
	s_addc_u32 vcc_hi, vcc_hi, 0
	s_cmp_ge_u32 s34, s18
	s_mov_b32 s68, s34
	s_cbranch_scc0 .LBB0_707
	s_and_b64 vcc, exec, s[50:51]
	s_cbranch_vccz .LBB0_710
	s_barrier
